# instruction-fetch alignment: the four GEMM K-loop headers aligned to 64 bytes
# speedup vs baseline: 1.0147x; 1.0034x over previous
; template <class Epi, class Sched, bool ALIGN_EPI = true, bool SP2 = true>
; __device__ __forceinline__ void gemm_phase(PG8_LAS unsigned char* lds, const Gemm g, const Sched& S, const Epi& E) {
;     ...
;     f32x4 acc[2][2][4][2];
; #pragma unroll
;     for (int a = 0; a < 2; ++a)
; #pragma unroll
;         for (int b = 0; b < 2; ++b)
; #pragma unroll
;             for (int m = 0; m < 4; ++m)
; #pragma unroll
;                 for (int n = 0; n < 2; ++n) acc[a][b][m][n] = (f32x4){0.f, 0.f, 0.f, 0.f};
;     bf16x8 At[4][2], B0[2][2], B1[2][2];
;     const char* cA = (const char*)g.A + (size_t)cur.pm * tstepA; const char* cB = (const char*)g.Bt + (size_t)cur.pn * tstepB;
;     if constexpr (SP2) {
;         PG8_STAGE(PG8_SB(0, 0), cB, voffB); PG8_STAGE(PG8_SB(0, 1), cB + hstepB, voffB); PG8_STAGE(PG8_SA(0, 0), cA, voffA); PG8_STAGE(PG8_SA(0, 1), cA + hstepA, voffA);
;         if (wr == 1) PG8_BAR;
;         PG8_WAIT_V(2); PG8_BAR;
;         PG8_STAGE(PG8_SB(1, 0), cB + kstep, voffB); PG8_STAGE(PG8_SA(1, 0), cA + kstep, voffA); PG8_STAGE(PG8_SB(1, 1), cB + hstepB + kstep, voffB);
;         PG8_WAIT_V(6); PG8_BAR;
;     } else {
;     PG8_STAGE(PG8_SB(0, 0), cB, voffB); PG8_STAGE(PG8_SA(0, 0), cA, voffA); PG8_STAGE(PG8_SB(0, 1), cB + hstepB, voffB); PG8_STAGE(PG8_SA(0, 1), cA + hstepA, voffA);
;     if (wr == 1) PG8_BAR;
;     PG8_WAIT_V(4); PG8_BAR;
;     PG8_STAGE(PG8_SB(1, 0), cB + kstep, voffB); PG8_STAGE(PG8_SA(1, 0), cA + kstep, voffA); PG8_STAGE(PG8_SB(1, 1), cB + hstepB + kstep, voffB);
;     PG8_WAIT_V(6); PG8_BAR;
;     }
;     for (;;) {
;         const bool has_next = S.next(ui + 1, nxt);
;         const char* nA = has_next ? (const char*)g.A + (size_t)nxt.pm * tstepA : cA; const char* nB = has_next ? (const char*)g.Bt + (size_t)nxt.pn * tstepB : cB;
;         for (int t = 0; t < nt; t += 2) {
;             const bool last = (t == nt - 2);
;             const char* a1 = PG8_ATILE(cA, t + 1);
;             const char* a2 = last ? nA : PG8_ATILE(cA, t + 2); const char* b2 = last ? nB : cB + (size_t)(t + 2) * kstep;
;             const char* a3 = a2 + kstep; const char* b3 = b2 + kstep;
;     ...
;         for (int a = 0; a < 2; ++a)
; #pragma unroll
;             for (int b = 0; b < 2; ++b)
; #pragma unroll
;                 for (int m = 0; m < 4; ++m)
; #pragma unroll
;                     for (int n = 0; n < 2; ++n) acc[a][b][m][n] = (f32x4){0.f, 0.f, 0.f, 0.f};
.LBB0_166:
	s_ashr_i32 s49, s48, 31
	s_lshl_b64 s[0:1], s[48:49], 19
	s_add_u32 s50, s58, s0
	s_addc_u32 s51, s35, s1
	s_and_b64 s[0:1], s[40:41], exec
	s_cselect_b32 s0, s51, s15
	s_cselect_b32 s1, s50, s14
	s_ashr_i32 s47, s46, 31
	s_lshl_b64 s[10:11], s[46:47], 19
	s_add_u32 s52, s60, s10
	s_addc_u32 s53, s59, s11
	s_and_b64 s[10:11], s[40:41], exec
	s_cselect_b32 s23, s53, s43
	s_cselect_b32 s26, s52, s42
	s_add_u32 s14, s14, 0x40080
	s_addc_u32 s15, s15, 0
	s_add_u32 s27, s42, 0x100
	v_mov_b32_e32 v0, 0
	s_addc_u32 s28, s43, 0
	s_mov_b32 s29, -2
	v_mov_b32_e32 v1, v0
	v_mov_b32_e32 v2, v0
	v_mov_b32_e32 v3, v0
	v_mov_b32_e32 v4, v0
	v_mov_b32_e32 v5, v0
	v_mov_b32_e32 v6, v0
	v_mov_b32_e32 v7, v0
	v_mov_b32_e32 v16, v0
	v_mov_b32_e32 v17, v0
	v_mov_b32_e32 v18, v0
	v_mov_b32_e32 v19, v0
	v_mov_b32_e32 v20, v0
	v_mov_b32_e32 v21, v0
	v_mov_b32_e32 v22, v0
	v_mov_b32_e32 v23, v0
	v_mov_b32_e32 v32, v0
	v_mov_b32_e32 v33, v0
	v_mov_b32_e32 v34, v0
	v_mov_b32_e32 v35, v0
	v_mov_b32_e32 v36, v0
	v_mov_b32_e32 v37, v0
	v_mov_b32_e32 v38, v0
	v_mov_b32_e32 v39, v0
	v_mov_b32_e32 v48, v0
	v_mov_b32_e32 v49, v0
	v_mov_b32_e32 v50, v0
	v_mov_b32_e32 v51, v0
	v_mov_b32_e32 v52, v0
	v_mov_b32_e32 v53, v0
	v_mov_b32_e32 v54, v0
	v_mov_b32_e32 v55, v0
	v_mov_b32_e32 v8, v0
	v_mov_b32_e32 v9, v0
	v_mov_b32_e32 v10, v0
	v_mov_b32_e32 v11, v0
	v_mov_b32_e32 v12, v0
	v_mov_b32_e32 v13, v0
	v_mov_b32_e32 v14, v0
	v_mov_b32_e32 v15, v0
	v_mov_b32_e32 v24, v0
	v_mov_b32_e32 v25, v0
	v_mov_b32_e32 v26, v0
	v_mov_b32_e32 v27, v0
	v_mov_b32_e32 v28, v0
	v_mov_b32_e32 v29, v0
	v_mov_b32_e32 v30, v0
	v_mov_b32_e32 v31, v0
	v_mov_b32_e32 v40, v0
	v_mov_b32_e32 v41, v0
	v_mov_b32_e32 v42, v0
	v_mov_b32_e32 v43, v0
	v_mov_b32_e32 v44, v0
	v_mov_b32_e32 v45, v0
	v_mov_b32_e32 v46, v0
	v_mov_b32_e32 v47, v0
	v_mov_b32_e32 v56, v0
	v_mov_b32_e32 v57, v0
	v_mov_b32_e32 v58, v0
	v_mov_b32_e32 v59, v0
	v_mov_b32_e32 v60, v0
	v_mov_b32_e32 v61, v0
	v_mov_b32_e32 v62, v0
	v_mov_b32_e32 v63, v0
	v_mov_b32_e32 v64, v0
	v_mov_b32_e32 v65, v0
	v_mov_b32_e32 v66, v0
	v_mov_b32_e32 v67, v0
	v_mov_b32_e32 v68, v0
	v_mov_b32_e32 v69, v0
	v_mov_b32_e32 v70, v0
	v_mov_b32_e32 v71, v0
	v_mov_b32_e32 v80, v0
	v_mov_b32_e32 v81, v0
	v_mov_b32_e32 v82, v0
	v_mov_b32_e32 v83, v0
	v_mov_b32_e32 v84, v0
	v_mov_b32_e32 v85, v0
	v_mov_b32_e32 v86, v0
	v_mov_b32_e32 v87, v0
	v_mov_b32_e32 v96, v0
	v_mov_b32_e32 v97, v0
	v_mov_b32_e32 v98, v0
	v_mov_b32_e32 v99, v0
	v_mov_b32_e32 v100, v0
	v_mov_b32_e32 v101, v0
	v_mov_b32_e32 v102, v0
	v_mov_b32_e32 v103, v0
	v_mov_b32_e32 v112, v0
	v_mov_b32_e32 v113, v0
	v_mov_b32_e32 v114, v0
	v_mov_b32_e32 v115, v0
	v_mov_b32_e32 v116, v0
	v_mov_b32_e32 v117, v0
	v_mov_b32_e32 v118, v0
	v_mov_b32_e32 v119, v0
	v_mov_b32_e32 v72, v0
	v_mov_b32_e32 v73, v0
	v_mov_b32_e32 v74, v0
	v_mov_b32_e32 v75, v0
	v_mov_b32_e32 v76, v0
	v_mov_b32_e32 v77, v0
	v_mov_b32_e32 v78, v0
	v_mov_b32_e32 v79, v0
	v_mov_b32_e32 v88, v0
	v_mov_b32_e32 v89, v0
	v_mov_b32_e32 v90, v0
	v_mov_b32_e32 v91, v0
	v_mov_b32_e32 v92, v0
	v_mov_b32_e32 v93, v0
	v_mov_b32_e32 v94, v0
	v_mov_b32_e32 v95, v0
	v_mov_b32_e32 v104, v0
	v_mov_b32_e32 v105, v0
	v_mov_b32_e32 v106, v0
	v_mov_b32_e32 v107, v0
	v_mov_b32_e32 v108, v0
	v_mov_b32_e32 v109, v0
	v_mov_b32_e32 v110, v0
	v_mov_b32_e32 v111, v0
	v_mov_b32_e32 v120, v0
	v_mov_b32_e32 v121, v0
	v_mov_b32_e32 v122, v0
	v_mov_b32_e32 v123, v0
	v_mov_b32_e32 v124, v0
	v_mov_b32_e32 v125, v0
	v_mov_b32_e32 v126, v0
	v_mov_b32_e32 v127, v0
	.p2align	6

; template <class Epi, class Sched, bool ALIGN_EPI = true, bool SP2 = true>
; __device__ __forceinline__ void gemm_phase(PG8_LAS unsigned char* lds, const Gemm g, const Sched& S, const Epi& E) {
;     ...
;     f32x4 acc[2][2][4][2];
; #pragma unroll
;     for (int a = 0; a < 2; ++a)
; #pragma unroll
;         for (int b = 0; b < 2; ++b)
; #pragma unroll
;             for (int m = 0; m < 4; ++m)
; #pragma unroll
;                 for (int n = 0; n < 2; ++n) acc[a][b][m][n] = (f32x4){0.f, 0.f, 0.f, 0.f};
;     bf16x8 At[4][2], B0[2][2], B1[2][2];
;     const char* cA = (const char*)g.A + (size_t)cur.pm * tstepA; const char* cB = (const char*)g.Bt + (size_t)cur.pn * tstepB;
;     if constexpr (SP2) {
;         PG8_STAGE(PG8_SB(0, 0), cB, voffB); PG8_STAGE(PG8_SB(0, 1), cB + hstepB, voffB); PG8_STAGE(PG8_SA(0, 0), cA, voffA); PG8_STAGE(PG8_SA(0, 1), cA + hstepA, voffA);
;         if (wr == 1) PG8_BAR;
;         PG8_WAIT_V(2); PG8_BAR;
;         PG8_STAGE(PG8_SB(1, 0), cB + kstep, voffB); PG8_STAGE(PG8_SA(1, 0), cA + kstep, voffA); PG8_STAGE(PG8_SB(1, 1), cB + hstepB + kstep, voffB);
;         PG8_WAIT_V(6); PG8_BAR;
;     } else {
;     PG8_STAGE(PG8_SB(0, 0), cB, voffB); PG8_STAGE(PG8_SA(0, 0), cA, voffA); PG8_STAGE(PG8_SB(0, 1), cB + hstepB, voffB); PG8_STAGE(PG8_SA(0, 1), cA + hstepA, voffA);
;     if (wr == 1) PG8_BAR;
;     PG8_WAIT_V(4); PG8_BAR;
;     PG8_STAGE(PG8_SB(1, 0), cB + kstep, voffB); PG8_STAGE(PG8_SA(1, 0), cA + kstep, voffA); PG8_STAGE(PG8_SB(1, 1), cB + hstepB + kstep, voffB);
;     PG8_WAIT_V(6); PG8_BAR;
;     }
;     for (;;) {
;         const bool has_next = S.next(ui + 1, nxt);
;         const char* nA = has_next ? (const char*)g.A + (size_t)nxt.pm * tstepA : cA; const char* nB = has_next ? (const char*)g.Bt + (size_t)nxt.pn * tstepB : cB;
;         for (int t = 0; t < nt; t += 2) {
;             const bool last = (t == nt - 2);
;             const char* a1 = PG8_ATILE(cA, t + 1);
;             const char* a2 = last ? nA : PG8_ATILE(cA, t + 2); const char* b2 = last ? nB : cB + (size_t)(t + 2) * kstep;
;             const char* a3 = a2 + kstep; const char* b3 = b2 + kstep;
;     ...
;         for (int a = 0; a < 2; ++a)
; #pragma unroll
;             for (int b = 0; b < 2; ++b)
; #pragma unroll
;                 for (int m = 0; m < 4; ++m)
; #pragma unroll
;                     for (int n = 0; n < 2; ++n) acc[a][b][m][n] = (f32x4){0.f, 0.f, 0.f, 0.f};
.LBB0_472:
	s_ashr_i32 s45, s44, 31
	s_lshl_b64 s[26:27], s[44:45], 19
	s_add_u32 s46, s78, s26
	s_addc_u32 s47, s79, s27
	s_and_b64 s[26:27], s[38:39], exec
	s_cselect_b32 s37, s47, s15
	s_cselect_b32 s45, s46, s14
	s_ashr_i32 s43, s42, 31
	s_lshl_b64 s[26:27], s[42:43], 19
	v_readlane_b32 s18, v254, 32
	s_add_u32 s48, s18, s26
	v_readlane_b32 s18, v254, 33
	s_addc_u32 s49, s18, s27
	s_and_b64 s[26:27], s[38:39], exec
	s_cselect_b32 s26, s49, s11
	s_cselect_b32 s27, s48, s10
	s_add_u32 s14, s14, 0x40080
	s_addc_u32 s15, s15, 0
	s_add_u32 s43, s10, 0x100
	v_mov_b32_e32 v0, 0
	s_addc_u32 s56, s11, 0
	s_mov_b32 s57, -2
	v_mov_b32_e32 v1, v0
	v_mov_b32_e32 v2, v0
	v_mov_b32_e32 v3, v0
	v_mov_b32_e32 v4, v0
	v_mov_b32_e32 v5, v0
	v_mov_b32_e32 v6, v0
	v_mov_b32_e32 v7, v0
	v_mov_b32_e32 v8, v0
	v_mov_b32_e32 v9, v0
	v_mov_b32_e32 v10, v0
	v_mov_b32_e32 v11, v0
	v_mov_b32_e32 v16, v0
	v_mov_b32_e32 v17, v0
	v_mov_b32_e32 v18, v0
	v_mov_b32_e32 v19, v0
	v_mov_b32_e32 v24, v0
	v_mov_b32_e32 v25, v0
	v_mov_b32_e32 v26, v0
	v_mov_b32_e32 v27, v0
	v_mov_b32_e32 v32, v0
	v_mov_b32_e32 v33, v0
	v_mov_b32_e32 v34, v0
	v_mov_b32_e32 v35, v0
	v_mov_b32_e32 v40, v0
	v_mov_b32_e32 v41, v0
	v_mov_b32_e32 v42, v0
	v_mov_b32_e32 v43, v0
	v_mov_b32_e32 v48, v0
	v_mov_b32_e32 v49, v0
	v_mov_b32_e32 v50, v0
	v_mov_b32_e32 v51, v0
	v_mov_b32_e32 v12, v0
	v_mov_b32_e32 v13, v0
	v_mov_b32_e32 v14, v0
	v_mov_b32_e32 v15, v0
	v_mov_b32_e32 v20, v0
	v_mov_b32_e32 v21, v0
	v_mov_b32_e32 v22, v0
	v_mov_b32_e32 v23, v0
	v_mov_b32_e32 v28, v0
	v_mov_b32_e32 v29, v0
	v_mov_b32_e32 v30, v0
	v_mov_b32_e32 v31, v0
	v_mov_b32_e32 v36, v0
	v_mov_b32_e32 v37, v0
	v_mov_b32_e32 v38, v0
	v_mov_b32_e32 v39, v0
	v_mov_b32_e32 v44, v0
	v_mov_b32_e32 v45, v0
	v_mov_b32_e32 v46, v0
	v_mov_b32_e32 v47, v0
	v_mov_b32_e32 v52, v0
	v_mov_b32_e32 v53, v0
	v_mov_b32_e32 v54, v0
	v_mov_b32_e32 v55, v0
	v_mov_b32_e32 v56, v0
	v_mov_b32_e32 v57, v0
	v_mov_b32_e32 v58, v0
	v_mov_b32_e32 v59, v0
	v_mov_b32_e32 v60, v0
	v_mov_b32_e32 v61, v0
	v_mov_b32_e32 v62, v0
	v_mov_b32_e32 v63, v0
	v_mov_b32_e32 v64, v0
	v_mov_b32_e32 v65, v0
	v_mov_b32_e32 v66, v0
	v_mov_b32_e32 v67, v0
	v_mov_b32_e32 v68, v0
	v_mov_b32_e32 v69, v0
	v_mov_b32_e32 v70, v0
	v_mov_b32_e32 v71, v0
	v_mov_b32_e32 v72, v0
	v_mov_b32_e32 v73, v0
	v_mov_b32_e32 v74, v0
	v_mov_b32_e32 v75, v0
	v_mov_b32_e32 v80, v0
	v_mov_b32_e32 v81, v0
	v_mov_b32_e32 v82, v0
	v_mov_b32_e32 v83, v0
	v_mov_b32_e32 v88, v0
	v_mov_b32_e32 v89, v0
	v_mov_b32_e32 v90, v0
	v_mov_b32_e32 v91, v0
	v_mov_b32_e32 v96, v0
	v_mov_b32_e32 v97, v0
	v_mov_b32_e32 v98, v0
	v_mov_b32_e32 v99, v0
	v_mov_b32_e32 v104, v0
	v_mov_b32_e32 v105, v0
	v_mov_b32_e32 v106, v0
	v_mov_b32_e32 v107, v0
	v_mov_b32_e32 v112, v0
	v_mov_b32_e32 v113, v0
	v_mov_b32_e32 v114, v0
	v_mov_b32_e32 v115, v0
	v_mov_b32_e32 v76, v0
	v_mov_b32_e32 v77, v0
	v_mov_b32_e32 v78, v0
	v_mov_b32_e32 v79, v0
	v_mov_b32_e32 v84, v0
	v_mov_b32_e32 v85, v0
	v_mov_b32_e32 v86, v0
	v_mov_b32_e32 v87, v0
	v_mov_b32_e32 v92, v0
	v_mov_b32_e32 v93, v0
	v_mov_b32_e32 v94, v0
	v_mov_b32_e32 v95, v0
	v_mov_b32_e32 v100, v0
	v_mov_b32_e32 v101, v0
	v_mov_b32_e32 v102, v0
	v_mov_b32_e32 v103, v0
	v_mov_b32_e32 v108, v0
	v_mov_b32_e32 v109, v0
	v_mov_b32_e32 v110, v0
	v_mov_b32_e32 v111, v0
	v_mov_b32_e32 v116, v0
	v_mov_b32_e32 v117, v0
	v_mov_b32_e32 v118, v0
	v_mov_b32_e32 v119, v0
	v_mov_b32_e32 v120, v0
	v_mov_b32_e32 v121, v0
	v_mov_b32_e32 v122, v0
	v_mov_b32_e32 v123, v0
	v_mov_b32_e32 v124, v0
	v_mov_b32_e32 v125, v0
	v_mov_b32_e32 v126, v0
	v_mov_b32_e32 v127, v0
	.p2align	6

; template <class Epi, class Sched, bool ALIGN_EPI = true, bool SP2 = true>
; __device__ __forceinline__ void gemm_phase(PG8_LAS unsigned char* lds, const Gemm g, const Sched& S, const Epi& E) {
;     ...
;     f32x4 acc[2][2][4][2];
; #pragma unroll
;     for (int a = 0; a < 2; ++a)
; #pragma unroll
;         for (int b = 0; b < 2; ++b)
; #pragma unroll
;             for (int m = 0; m < 4; ++m)
; #pragma unroll
;                 for (int n = 0; n < 2; ++n) acc[a][b][m][n] = (f32x4){0.f, 0.f, 0.f, 0.f};
;     bf16x8 At[4][2], B0[2][2], B1[2][2];
;     const char* cA = (const char*)g.A + (size_t)cur.pm * tstepA; const char* cB = (const char*)g.Bt + (size_t)cur.pn * tstepB;
;     if constexpr (SP2) {
;         PG8_STAGE(PG8_SB(0, 0), cB, voffB); PG8_STAGE(PG8_SB(0, 1), cB + hstepB, voffB); PG8_STAGE(PG8_SA(0, 0), cA, voffA); PG8_STAGE(PG8_SA(0, 1), cA + hstepA, voffA);
;         if (wr == 1) PG8_BAR;
;         PG8_WAIT_V(2); PG8_BAR;
;         PG8_STAGE(PG8_SB(1, 0), cB + kstep, voffB); PG8_STAGE(PG8_SA(1, 0), cA + kstep, voffA); PG8_STAGE(PG8_SB(1, 1), cB + hstepB + kstep, voffB);
;         PG8_WAIT_V(6); PG8_BAR;
;     } else {
;     PG8_STAGE(PG8_SB(0, 0), cB, voffB); PG8_STAGE(PG8_SA(0, 0), cA, voffA); PG8_STAGE(PG8_SB(0, 1), cB + hstepB, voffB); PG8_STAGE(PG8_SA(0, 1), cA + hstepA, voffA);
;     if (wr == 1) PG8_BAR;
;     PG8_WAIT_V(4); PG8_BAR;
;     PG8_STAGE(PG8_SB(1, 0), cB + kstep, voffB); PG8_STAGE(PG8_SA(1, 0), cA + kstep, voffA); PG8_STAGE(PG8_SB(1, 1), cB + hstepB + kstep, voffB);
;     PG8_WAIT_V(6); PG8_BAR;
;     }
;     for (;;) {
;         const bool has_next = S.next(ui + 1, nxt);
;         const char* nA = has_next ? (const char*)g.A + (size_t)nxt.pm * tstepA : cA; const char* nB = has_next ? (const char*)g.Bt + (size_t)nxt.pn * tstepB : cB;
;         for (int t = 0; t < nt; t += 2) {
;             const bool last = (t == nt - 2);
;             const char* a1 = PG8_ATILE(cA, t + 1);
;             const char* a2 = last ? nA : PG8_ATILE(cA, t + 2); const char* b2 = last ? nB : cB + (size_t)(t + 2) * kstep;
;             const char* a3 = a2 + kstep; const char* b3 = b2 + kstep;
;     ...
;         for (int a = 0; a < 2; ++a)
; #pragma unroll
;             for (int b = 0; b < 2; ++b)
; #pragma unroll
;                 for (int m = 0; m < 4; ++m)
; #pragma unroll
;                     for (int n = 0; n < 2; ++n) acc[a][b][m][n] = (f32x4){0.f, 0.f, 0.f, 0.f};
.LBB0_689:
	s_ashr_i32 s47, s46, 31
	s_lshl_b64 s[10:11], s[46:47], s57
	s_add_u32 s48, s54, s10
	s_addc_u32 s49, s35, s11
	s_and_b64 s[10:11], s[38:39], exec
	s_cselect_b32 s47, s49, s15
	s_cselect_b32 vcc_lo, s48, s14
	s_ashr_i32 s45, s44, 31
	s_lshl_b64 s[10:11], s[44:45], s58
	s_add_u32 s50, s17, s10
	s_addc_u32 s51, s12, s11
	s_and_b64 s[10:11], s[38:39], exec
	s_cselect_b32 s45, s51, s53
	s_cselect_b32 vcc_hi, s50, s52
	s_add_u32 s14, s14, 0x80
	s_addc_u32 s15, s15, 0
	s_add_u32 s52, s52, 0x100
	v_mov_b32_e32 v0, 0
	s_addc_u32 s53, s53, 0
	s_mov_b32 s26, 0
	s_mov_b32 s27, s1
	v_mov_b32_e32 v1, v0
	v_mov_b32_e32 v2, v0
	v_mov_b32_e32 v3, v0
	v_mov_b32_e32 v4, v0
	v_mov_b32_e32 v5, v0
	v_mov_b32_e32 v6, v0
	v_mov_b32_e32 v7, v0
	v_mov_b32_e32 v8, v0
	v_mov_b32_e32 v9, v0
	v_mov_b32_e32 v10, v0
	v_mov_b32_e32 v11, v0
	v_mov_b32_e32 v16, v0
	v_mov_b32_e32 v17, v0
	v_mov_b32_e32 v18, v0
	v_mov_b32_e32 v19, v0
	v_mov_b32_e32 v24, v0
	v_mov_b32_e32 v25, v0
	v_mov_b32_e32 v26, v0
	v_mov_b32_e32 v27, v0
	v_mov_b32_e32 v32, v0
	v_mov_b32_e32 v33, v0
	v_mov_b32_e32 v34, v0
	v_mov_b32_e32 v35, v0
	v_mov_b32_e32 v40, v0
	v_mov_b32_e32 v41, v0
	v_mov_b32_e32 v42, v0
	v_mov_b32_e32 v43, v0
	v_mov_b32_e32 v48, v0
	v_mov_b32_e32 v49, v0
	v_mov_b32_e32 v50, v0
	v_mov_b32_e32 v51, v0
	v_mov_b32_e32 v12, v0
	v_mov_b32_e32 v13, v0
	v_mov_b32_e32 v14, v0
	v_mov_b32_e32 v15, v0
	v_mov_b32_e32 v20, v0
	v_mov_b32_e32 v21, v0
	v_mov_b32_e32 v22, v0
	v_mov_b32_e32 v23, v0
	v_mov_b32_e32 v28, v0
	v_mov_b32_e32 v29, v0
	v_mov_b32_e32 v30, v0
	v_mov_b32_e32 v31, v0
	v_mov_b32_e32 v36, v0
	v_mov_b32_e32 v37, v0
	v_mov_b32_e32 v38, v0
	v_mov_b32_e32 v39, v0
	v_mov_b32_e32 v44, v0
	v_mov_b32_e32 v45, v0
	v_mov_b32_e32 v46, v0
	v_mov_b32_e32 v47, v0
	v_mov_b32_e32 v52, v0
	v_mov_b32_e32 v53, v0
	v_mov_b32_e32 v54, v0
	v_mov_b32_e32 v55, v0
	v_mov_b32_e32 v56, v0
	v_mov_b32_e32 v57, v0
	v_mov_b32_e32 v58, v0
	v_mov_b32_e32 v59, v0
	v_mov_b32_e32 v60, v0
	v_mov_b32_e32 v61, v0
	v_mov_b32_e32 v62, v0
	v_mov_b32_e32 v63, v0
	v_mov_b32_e32 v64, v0
	v_mov_b32_e32 v65, v0
	v_mov_b32_e32 v66, v0
	v_mov_b32_e32 v67, v0
	v_mov_b32_e32 v68, v0
	v_mov_b32_e32 v69, v0
	v_mov_b32_e32 v70, v0
	v_mov_b32_e32 v71, v0
	v_mov_b32_e32 v72, v0
	v_mov_b32_e32 v73, v0
	v_mov_b32_e32 v74, v0
	v_mov_b32_e32 v75, v0
	v_mov_b32_e32 v80, v0
	v_mov_b32_e32 v81, v0
	v_mov_b32_e32 v82, v0
	v_mov_b32_e32 v83, v0
	v_mov_b32_e32 v88, v0
	v_mov_b32_e32 v89, v0
	v_mov_b32_e32 v90, v0
	v_mov_b32_e32 v91, v0
	v_mov_b32_e32 v96, v0
	v_mov_b32_e32 v97, v0
	v_mov_b32_e32 v98, v0
	v_mov_b32_e32 v99, v0
	v_mov_b32_e32 v104, v0
	v_mov_b32_e32 v105, v0
	v_mov_b32_e32 v106, v0
	v_mov_b32_e32 v107, v0
	v_mov_b32_e32 v112, v0
	v_mov_b32_e32 v113, v0
	v_mov_b32_e32 v114, v0
	v_mov_b32_e32 v115, v0
	v_mov_b32_e32 v76, v0
	v_mov_b32_e32 v77, v0
	v_mov_b32_e32 v78, v0
	v_mov_b32_e32 v79, v0
	v_mov_b32_e32 v84, v0
	v_mov_b32_e32 v85, v0
	v_mov_b32_e32 v86, v0
	v_mov_b32_e32 v87, v0
	v_mov_b32_e32 v92, v0
	v_mov_b32_e32 v93, v0
	v_mov_b32_e32 v94, v0
	v_mov_b32_e32 v95, v0
	v_mov_b32_e32 v100, v0
	v_mov_b32_e32 v101, v0
	v_mov_b32_e32 v102, v0
	v_mov_b32_e32 v103, v0
	v_mov_b32_e32 v108, v0
	v_mov_b32_e32 v109, v0
	v_mov_b32_e32 v110, v0
	v_mov_b32_e32 v111, v0
	v_mov_b32_e32 v116, v0
	v_mov_b32_e32 v117, v0
	v_mov_b32_e32 v118, v0
	v_mov_b32_e32 v119, v0
	v_mov_b32_e32 v120, v0
	v_mov_b32_e32 v121, v0
	v_mov_b32_e32 v122, v0
	v_mov_b32_e32 v123, v0
	v_mov_b32_e32 v124, v0
	v_mov_b32_e32 v125, v0
	v_mov_b32_e32 v126, v0
	v_mov_b32_e32 v127, v0
	.p2align	6

; template <class Epi, class Sched, bool ALIGN_EPI = true, bool SP2 = true>
; __device__ __forceinline__ void gemm_phase(PG8_LAS unsigned char* lds, const Gemm g, const Sched& S, const Epi& E) {
;     ...
;     f32x4 acc[2][2][4][2];
; #pragma unroll
;     for (int a = 0; a < 2; ++a)
; #pragma unroll
;         for (int b = 0; b < 2; ++b)
; #pragma unroll
;             for (int m = 0; m < 4; ++m)
; #pragma unroll
;                 for (int n = 0; n < 2; ++n) acc[a][b][m][n] = (f32x4){0.f, 0.f, 0.f, 0.f};
;     bf16x8 At[4][2], B0[2][2], B1[2][2];
;     const char* cA = (const char*)g.A + (size_t)cur.pm * tstepA; const char* cB = (const char*)g.Bt + (size_t)cur.pn * tstepB;
;     if constexpr (SP2) {
;         PG8_STAGE(PG8_SB(0, 0), cB, voffB); PG8_STAGE(PG8_SB(0, 1), cB + hstepB, voffB); PG8_STAGE(PG8_SA(0, 0), cA, voffA); PG8_STAGE(PG8_SA(0, 1), cA + hstepA, voffA);
;         if (wr == 1) PG8_BAR;
;         PG8_WAIT_V(2); PG8_BAR;
;         PG8_STAGE(PG8_SB(1, 0), cB + kstep, voffB); PG8_STAGE(PG8_SA(1, 0), cA + kstep, voffA); PG8_STAGE(PG8_SB(1, 1), cB + hstepB + kstep, voffB);
;         PG8_WAIT_V(6); PG8_BAR;
;     } else {
;     PG8_STAGE(PG8_SB(0, 0), cB, voffB); PG8_STAGE(PG8_SA(0, 0), cA, voffA); PG8_STAGE(PG8_SB(0, 1), cB + hstepB, voffB); PG8_STAGE(PG8_SA(0, 1), cA + hstepA, voffA);
;     if (wr == 1) PG8_BAR;
;     PG8_WAIT_V(4); PG8_BAR;
;     PG8_STAGE(PG8_SB(1, 0), cB + kstep, voffB); PG8_STAGE(PG8_SA(1, 0), cA + kstep, voffA); PG8_STAGE(PG8_SB(1, 1), cB + hstepB + kstep, voffB);
;     PG8_WAIT_V(6); PG8_BAR;
;     }
;     for (;;) {
;         const bool has_next = S.next(ui + 1, nxt);
;         const char* nA = has_next ? (const char*)g.A + (size_t)nxt.pm * tstepA : cA; const char* nB = has_next ? (const char*)g.Bt + (size_t)nxt.pn * tstepB : cB;
;         for (int t = 0; t < nt; t += 2) {
;             const bool last = (t == nt - 2);
;             const char* a1 = PG8_ATILE(cA, t + 1);
;             const char* a2 = last ? nA : PG8_ATILE(cA, t + 2); const char* b2 = last ? nB : cB + (size_t)(t + 2) * kstep;
;             const char* a3 = a2 + kstep; const char* b3 = b2 + kstep;
;     ...
;         for (int a = 0; a < 2; ++a)
; #pragma unroll
;             for (int b = 0; b < 2; ++b)
; #pragma unroll
;                 for (int m = 0; m < 4; ++m)
; #pragma unroll
;                     for (int n = 0; n < 2; ++n) acc[a][b][m][n] = (f32x4){0.f, 0.f, 0.f, 0.f};
.LBB0_855:
	s_ashr_i32 s49, s48, 31
	s_lshl_b64 s[24:25], s[48:49], 19
	s_add_u32 s50, s78, s24
	s_addc_u32 s51, s79, s25
	s_and_b64 s[24:25], s[38:39], exec
	s_cselect_b32 s23, s51, s15
	s_cselect_b32 s28, s50, s14
	s_ashr_i32 s47, s46, 31
	s_lshl_b64 s[24:25], s[46:47], 19
	v_readlane_b32 s18, v254, 49
	v_readlane_b32 s19, v254, 50
	s_add_u32 s52, s18, s24
	s_addc_u32 s53, s19, s25
	s_and_b64 s[24:25], s[38:39], exec
	s_cselect_b32 s26, s53, s11
	s_cselect_b32 s27, s52, s10
	s_add_u32 s14, s14, 0x40080
	s_addc_u32 s15, s15, 0
	s_add_u32 s29, s10, 0x100
	v_mov_b32_e32 v0, 0
	s_addc_u32 s37, s11, 0
	s_mov_b32 s47, -2
	v_mov_b32_e32 v1, v0
	v_mov_b32_e32 v2, v0
	v_mov_b32_e32 v3, v0
	v_mov_b32_e32 v4, v0
	v_mov_b32_e32 v5, v0
	v_mov_b32_e32 v6, v0
	v_mov_b32_e32 v7, v0
	v_mov_b32_e32 v16, v0
	v_mov_b32_e32 v17, v0
	v_mov_b32_e32 v18, v0
	v_mov_b32_e32 v19, v0
	v_mov_b32_e32 v20, v0
	v_mov_b32_e32 v21, v0
	v_mov_b32_e32 v22, v0
	v_mov_b32_e32 v23, v0
	v_mov_b32_e32 v32, v0
	v_mov_b32_e32 v33, v0
	v_mov_b32_e32 v34, v0
	v_mov_b32_e32 v35, v0
	v_mov_b32_e32 v36, v0
	v_mov_b32_e32 v37, v0
	v_mov_b32_e32 v38, v0
	v_mov_b32_e32 v39, v0
	v_mov_b32_e32 v48, v0
	v_mov_b32_e32 v49, v0
	v_mov_b32_e32 v50, v0
	v_mov_b32_e32 v51, v0
	v_mov_b32_e32 v52, v0
	v_mov_b32_e32 v53, v0
	v_mov_b32_e32 v54, v0
	v_mov_b32_e32 v55, v0
	v_mov_b32_e32 v8, v0
	v_mov_b32_e32 v9, v0
	v_mov_b32_e32 v10, v0
	v_mov_b32_e32 v11, v0
	v_mov_b32_e32 v12, v0
	v_mov_b32_e32 v13, v0
	v_mov_b32_e32 v14, v0
	v_mov_b32_e32 v15, v0
	v_mov_b32_e32 v24, v0
	v_mov_b32_e32 v25, v0
	v_mov_b32_e32 v26, v0
	v_mov_b32_e32 v27, v0
	v_mov_b32_e32 v28, v0
	v_mov_b32_e32 v29, v0
	v_mov_b32_e32 v30, v0
	v_mov_b32_e32 v31, v0
	v_mov_b32_e32 v40, v0
	v_mov_b32_e32 v41, v0
	v_mov_b32_e32 v42, v0
	v_mov_b32_e32 v43, v0
	v_mov_b32_e32 v44, v0
	v_mov_b32_e32 v45, v0
	v_mov_b32_e32 v46, v0
	v_mov_b32_e32 v47, v0
	v_mov_b32_e32 v56, v0
	v_mov_b32_e32 v57, v0
	v_mov_b32_e32 v58, v0
	v_mov_b32_e32 v59, v0
	v_mov_b32_e32 v60, v0
	v_mov_b32_e32 v61, v0
	v_mov_b32_e32 v62, v0
	v_mov_b32_e32 v63, v0
	v_mov_b32_e32 v64, v0
	v_mov_b32_e32 v65, v0
	v_mov_b32_e32 v66, v0
	v_mov_b32_e32 v67, v0
	v_mov_b32_e32 v68, v0
	v_mov_b32_e32 v69, v0
	v_mov_b32_e32 v70, v0
	v_mov_b32_e32 v71, v0
	v_mov_b32_e32 v80, v0
	v_mov_b32_e32 v81, v0
	v_mov_b32_e32 v82, v0
	v_mov_b32_e32 v83, v0
	v_mov_b32_e32 v84, v0
	v_mov_b32_e32 v85, v0
	v_mov_b32_e32 v86, v0
	v_mov_b32_e32 v87, v0
	v_mov_b32_e32 v96, v0
	v_mov_b32_e32 v97, v0
	v_mov_b32_e32 v98, v0
	v_mov_b32_e32 v99, v0
	v_mov_b32_e32 v100, v0
	v_mov_b32_e32 v101, v0
	v_mov_b32_e32 v102, v0
	v_mov_b32_e32 v103, v0
	v_mov_b32_e32 v112, v0
	v_mov_b32_e32 v113, v0
	v_mov_b32_e32 v114, v0
	v_mov_b32_e32 v115, v0
	v_mov_b32_e32 v124, v0
	v_mov_b32_e32 v125, v0
	v_mov_b32_e32 v126, v0
	v_mov_b32_e32 v127, v0
	v_mov_b32_e32 v72, v0
	v_mov_b32_e32 v73, v0
	v_mov_b32_e32 v74, v0
	v_mov_b32_e32 v75, v0
	v_mov_b32_e32 v76, v0
	v_mov_b32_e32 v77, v0
	v_mov_b32_e32 v78, v0
	v_mov_b32_e32 v79, v0
	v_mov_b32_e32 v88, v0
	v_mov_b32_e32 v89, v0
	v_mov_b32_e32 v90, v0
	v_mov_b32_e32 v91, v0
	v_mov_b32_e32 v92, v0
	v_mov_b32_e32 v93, v0
	v_mov_b32_e32 v94, v0
	v_mov_b32_e32 v95, v0
	v_mov_b32_e32 v104, v0
	v_mov_b32_e32 v105, v0
	v_mov_b32_e32 v106, v0
	v_mov_b32_e32 v107, v0
	v_mov_b32_e32 v108, v0
	v_mov_b32_e32 v109, v0
	v_mov_b32_e32 v110, v0
	v_mov_b32_e32 v111, v0
	v_mov_b32_e32 v136, v0
	v_mov_b32_e32 v137, v0
	v_mov_b32_e32 v138, v0
	v_mov_b32_e32 v139, v0
	v_mov_b32_e32 v148, v0
	v_mov_b32_e32 v149, v0
	v_mov_b32_e32 v150, v0
	v_mov_b32_e32 v151, v0
	.p2align	6
